# v24 with 8 Toeplitz iterations in flight per wave instead of 4
# baseline (speedup 1.0000x reference)
; __device__ void phase_ymat_toeplitz(PP P, int wid) {
;     ...
;     for (size_t it = (size_t)blockIdx.x * NTHREADS + tidx; it < total; it += (size_t)gridDim.x * NTHREADS) {
;         const int k8 = (int)(it & 63) * 8, n = (int)(it >> 6) & 511, jg = (int)(it >> 15);
;         const int t = n >> 4, i = n & 15, s = k8 >> 4, j0 = k8 & 15;
;         const float* kf = ktab + ((size_t)jg * 2 + 0) * 32 * 256, *kb = ktab + ((size_t)jg * 2 + 1) * 32 * 256;
;         float f[8];
;         if (s < t) { load8f(kf + (t - s) * 256 + i * 16 + j0, f); }
;         else if (s > t) { load8f(kb + (s - t) * 256 + i * 16 + j0, f); }
;         else { float a[8], b[8]; load8f(kf + i * 16 + j0, a); load8f(kb + i * 16 + j0, b);
;             const int j = jg >> 6, g = jg & 63; const float dsk = P->in[21][j * D + g * 16 + i];
; #pragma unroll
;             for (int q = 0; q < 8; ++q) f[q] = a[q] + b[q] + ((j0 + q) == i ? dsk : 0.f); }
;         *(u32x4*)((bf16_t*)(P->ws + WS_YMAT) + ((size_t)jg * 512 + n) * XLD + k8) = pack8(f);
;     }
.LBB0_96:
	s_or_b64 exec, exec, s[4:5]
	v_readlane_b32 s80, v255, 0
	v_readlane_b32 s81, v255, 1
	s_mov_b64 s[4:5], s[80:81]
	s_barrier
	v_mbcnt_lo_u32_b32 v0, -1, 0
	v_mbcnt_hi_u32_b32 v0, -1, v0
	s_load_dwordx2 s[6:7], s[4:5], 0xe0
	v_add_u32_e32 v2, s82, v0
	s_mov_b32 s3, 0
	s_lshl_b64 s[8:9], s[2:3], 9
	v_ashrrev_i32_e32 v3, 31, v2
	v_lshl_add_u64 v[8:9], s[8:9], 0, v[2:3]
	s_mov_b64 s[0:1], 0x400000
	v_cmp_gt_u64_e32 vcc, s[0:1], v[8:9]
	s_and_saveexec_b64 s[10:11], vcc
	s_cbranch_execz .LBB0_107
	s_cmp_lg_u32 s14, 0x100
	s_cbranch_scc1 .Ltp_orig
	s_load_dwordx2 s[30:31], s[4:5], 0xa8
	v_mbcnt_lo_u32_b32 v0, -1, 0
	v_mbcnt_hi_u32_b32 v0, -1, v0
	s_lshr_b32 s0, s82, 6
	s_lshl_b32 s1, s2, 3
	s_add_i32 s0, s1, s0
	s_and_b32 s1, s0, 0x1ff
	s_lshr_b32 s20, s2, 6
	s_lshr_b32 s21, s1, 4
	s_and_b32 s22, s1, 15
	v_lshrrev_b32_e32 v1, 1, v0
	v_and_b32_e32 v8, 1, v0
	v_lshlrev_b32_e32 v2, 5, v8
	v_lshlrev_b32_e32 v8, 3, v8
	s_lshl_b32 s23, s22, 6
	v_add_u32_e32 v2, s23, v2
	v_sub_u32_e32 v3, s21, v1
	v_subrev_u32_e32 v4, s21, v1
	v_cmp_ge_u32_e32 vcc, s21, v1
	v_lshl_add_u32 v5, v3, 10, v2
	v_lshl_add_u32 v6, v4, 10, v2
	v_add_u32_e32 v6, 0x8000, v6
	v_add_u32_e32 v7, 0x8000, v2
	v_cmp_eq_u32_e64 s[24:25], s21, v1
	v_cndmask_b32_e32 v5, v6, v5, vcc
	v_lshlrev_b32_e32 v10, 4, v0
	v_mov_b32_e32 v11, 0
	v_add_u32_e32 v9, 0, v8
	v_cmp_eq_u32_e32 vcc, s22, v9
	s_nop 1
	v_cndmask_b32_e64 v12, 0, 1.0, vcc
	v_add_u32_e32 v9, 1, v8
	v_cmp_eq_u32_e32 vcc, s22, v9
	s_nop 1
	v_cndmask_b32_e64 v13, 0, 1.0, vcc
	v_add_u32_e32 v9, 2, v8
	v_cmp_eq_u32_e32 vcc, s22, v9
	s_nop 1
	v_cndmask_b32_e64 v14, 0, 1.0, vcc
	v_add_u32_e32 v9, 3, v8
	v_cmp_eq_u32_e32 vcc, s22, v9
	s_nop 1
	v_cndmask_b32_e64 v15, 0, 1.0, vcc
	v_add_u32_e32 v9, 4, v8
	v_cmp_eq_u32_e32 vcc, s22, v9
	s_nop 1
	v_cndmask_b32_e64 v16, 0, 1.0, vcc
	v_add_u32_e32 v9, 5, v8
	v_cmp_eq_u32_e32 vcc, s22, v9
	s_nop 1
	v_cndmask_b32_e64 v17, 0, 1.0, vcc
	v_add_u32_e32 v9, 6, v8
	v_cmp_eq_u32_e32 vcc, s22, v9
	s_nop 1
	v_cndmask_b32_e64 v18, 0, 1.0, vcc
	v_add_u32_e32 v9, 7, v8
	v_cmp_eq_u32_e32 vcc, s22, v9
	s_nop 1
	v_cndmask_b32_e64 v19, 0, 1.0, vcc
	s_waitcnt lgkmcnt(0)
	s_lshl_b32 s0, s20, 16
	s_add_u32 s16, s6, 0x9800000
	s_addc_u32 s17, s7, 0
	s_add_u32 s16, s16, s0
	s_addc_u32 s17, s17, 0
	s_mul_i32 s0, s20, 0xc0000
	s_mul_i32 s1, s1, 0x600
	s_add_i32 s0, s0, s1
	s_add_u32 s18, s6, 0x3800000
	s_addc_u32 s19, s7, 0
	s_add_u32 s18, s18, s0
	s_addc_u32 s19, s19, 0
	s_lshl_b32 s0, s20, 4
	s_add_i32 s0, s0, s22
	s_lshl_b32 s0, s0, 2
	s_add_u32 s30, s30, s0
	s_addc_u32 s31, s31, 0
	s_mov_b32 s13, 0
	s_mul_i32 s0, s13, 0x40000
	s_add_u32 s26, s16, s0
	s_addc_u32 s27, s17, 0
	s_lshl_b32 s0, s13, 8
	s_add_u32 s28, s30, s0
	s_addc_u32 s29, s31, 0
	global_load_dwordx4 v[24:27], v5, s[26:27]
	global_load_dwordx4 v[28:31], v5, s[26:27] offset:16
	s_mov_b64 exec, s[24:25]
	global_load_dwordx4 v[32:35], v7, s[26:27]
	global_load_dwordx4 v[36:39], v7, s[26:27] offset:16
	global_load_dword v40, v11, s[28:29]
	s_mov_b64 exec, -1
	s_mov_b32 s23, 1
	s_mul_i32 s0, s23, 0x40000
	s_add_u32 s26, s16, s0
	s_addc_u32 s27, s17, 0
	s_lshl_b32 s0, s23, 8
	s_add_u32 s28, s30, s0
	s_addc_u32 s29, s31, 0
	global_load_dwordx4 v[42:45], v5, s[26:27]
	global_load_dwordx4 v[46:49], v5, s[26:27] offset:16
	s_mov_b64 exec, s[24:25]
	global_load_dwordx4 v[50:53], v7, s[26:27]
	global_load_dwordx4 v[54:57], v7, s[26:27] offset:16
	global_load_dword v58, v11, s[28:29]
	s_mov_b64 exec, -1
	s_mov_b32 s23, 2
	s_mul_i32 s0, s23, 0x40000
	s_add_u32 s26, s16, s0
	s_addc_u32 s27, s17, 0
	s_lshl_b32 s0, s23, 8
	s_add_u32 s28, s30, s0
	s_addc_u32 s29, s31, 0
	global_load_dwordx4 v[60:63], v5, s[26:27]
	global_load_dwordx4 v[64:67], v5, s[26:27] offset:16
	s_mov_b64 exec, s[24:25]
	global_load_dwordx4 v[68:71], v7, s[26:27]
	global_load_dwordx4 v[72:75], v7, s[26:27] offset:16
	global_load_dword v76, v11, s[28:29]
	s_mov_b64 exec, -1
	s_mov_b32 s23, 3
	s_mul_i32 s0, s23, 0x40000
	s_add_u32 s26, s16, s0
	s_addc_u32 s27, s17, 0
	s_lshl_b32 s0, s23, 8
	s_add_u32 s28, s30, s0
	s_addc_u32 s29, s31, 0
	global_load_dwordx4 v[78:81], v5, s[26:27]
	global_load_dwordx4 v[82:85], v5, s[26:27] offset:16
	s_mov_b64 exec, s[24:25]
	global_load_dwordx4 v[86:89], v7, s[26:27]
	global_load_dwordx4 v[90:93], v7, s[26:27] offset:16
	global_load_dword v94, v11, s[28:29]
	s_mov_b64 exec, -1
	s_mov_b32 s23, 4
	s_mul_i32 s0, s23, 0x40000
	s_add_u32 s26, s16, s0
	s_addc_u32 s27, s17, 0
	s_lshl_b32 s0, s23, 8
	s_add_u32 s28, s30, s0
	s_addc_u32 s29, s31, 0
	global_load_dwordx4 v[96:99], v5, s[26:27]
	global_load_dwordx4 v[100:103], v5, s[26:27] offset:16
	s_mov_b64 exec, s[24:25]
	global_load_dwordx4 v[104:107], v7, s[26:27]
	global_load_dwordx4 v[108:111], v7, s[26:27] offset:16
	global_load_dword v112, v11, s[28:29]
	s_mov_b64 exec, -1
	s_mov_b32 s23, 5
	s_mul_i32 s0, s23, 0x40000
	s_add_u32 s26, s16, s0
	s_addc_u32 s27, s17, 0
	s_lshl_b32 s0, s23, 8
	s_add_u32 s28, s30, s0
	s_addc_u32 s29, s31, 0
	global_load_dwordx4 v[114:117], v5, s[26:27]
	global_load_dwordx4 v[118:121], v5, s[26:27] offset:16
	s_mov_b64 exec, s[24:25]
	global_load_dwordx4 v[122:125], v7, s[26:27]
	global_load_dwordx4 v[126:129], v7, s[26:27] offset:16
	global_load_dword v130, v11, s[28:29]
	s_mov_b64 exec, -1
	s_mov_b32 s23, 6
	s_mul_i32 s0, s23, 0x40000
	s_add_u32 s26, s16, s0
	s_addc_u32 s27, s17, 0
	s_lshl_b32 s0, s23, 8
	s_add_u32 s28, s30, s0
	s_addc_u32 s29, s31, 0
	global_load_dwordx4 v[132:135], v5, s[26:27]
	global_load_dwordx4 v[136:139], v5, s[26:27] offset:16
	s_mov_b64 exec, s[24:25]
	global_load_dwordx4 v[140:143], v7, s[26:27]
	global_load_dwordx4 v[144:147], v7, s[26:27] offset:16
	global_load_dword v148, v11, s[28:29]
	s_mov_b64 exec, -1
	s_mov_b32 s23, 7
	s_mul_i32 s0, s23, 0x40000
	s_add_u32 s26, s16, s0
	s_addc_u32 s27, s17, 0
	s_lshl_b32 s0, s23, 8
	s_add_u32 s28, s30, s0
	s_addc_u32 s29, s31, 0
	global_load_dwordx4 v[150:153], v5, s[26:27]
	global_load_dwordx4 v[154:157], v5, s[26:27] offset:16
	s_mov_b64 exec, s[24:25]
	global_load_dwordx4 v[158:161], v7, s[26:27]
	global_load_dwordx4 v[162:165], v7, s[26:27] offset:16
	global_load_dword v166, v11, s[28:29]
	s_mov_b64 exec, -1
	s_waitcnt vmcnt(35)
; __device__ void phase_ymat_toeplitz(PP P, int wid) {
;     ...
;     for (size_t it = (size_t)blockIdx.x * NTHREADS + tidx; it < total; it += (size_t)gridDim.x * NTHREADS) {
;         const int k8 = (int)(it & 63) * 8, n = (int)(it >> 6) & 511, jg = (int)(it >> 15);
;         const int t = n >> 4, i = n & 15, s = k8 >> 4, j0 = k8 & 15;
;         const float* kf = ktab + ((size_t)jg * 2 + 0) * 32 * 256, *kb = ktab + ((size_t)jg * 2 + 1) * 32 * 256;
;         float f[8];
;         if (s < t) { load8f(kf + (t - s) * 256 + i * 16 + j0, f); }
;         else if (s > t) { load8f(kb + (s - t) * 256 + i * 16 + j0, f); }
;         else { float a[8], b[8]; load8f(kf + i * 16 + j0, a); load8f(kb + i * 16 + j0, b);
;             const int j = jg >> 6, g = jg & 63; const float dsk = P->in[21][j * D + g * 16 + i];
; #pragma unroll
;             for (int q = 0; q < 8; ++q) f[q] = a[q] + b[q] + ((j0 + q) == i ? dsk : 0.f); }
;         *(u32x4*)((bf16_t*)(P->ws + WS_YMAT) + ((size_t)jg * 512 + n) * XLD + k8) = pack8(f);
;     }
	s_mov_b64 exec, s[24:25]
	v_pk_add_f32 v[24:25], v[24:25], v[32:33]
	v_pk_add_f32 v[26:27], v[26:27], v[34:35]
	v_pk_add_f32 v[28:29], v[28:29], v[36:37]
	v_pk_add_f32 v[30:31], v[30:31], v[38:39]
	v_pk_fma_f32 v[24:25], v[12:13], v[40:41], v[24:25] op_sel_hi:[1,0,1]
	v_pk_fma_f32 v[26:27], v[14:15], v[40:41], v[26:27] op_sel_hi:[1,0,1]
	v_pk_fma_f32 v[28:29], v[16:17], v[40:41], v[28:29] op_sel_hi:[1,0,1]
	v_pk_fma_f32 v[30:31], v[18:19], v[40:41], v[30:31] op_sel_hi:[1,0,1]
	s_mov_b64 exec, -1
	s_nop 0
	v_cvt_pk_bf16_f32 v20, v24, v25
	v_cvt_pk_bf16_f32 v21, v26, v27
	v_cvt_pk_bf16_f32 v22, v28, v29
	v_cvt_pk_bf16_f32 v23, v30, v31
	s_mul_i32 s0, s13, 0x300000
	s_add_u32 s26, s18, s0
	s_addc_u32 s27, s19, 0
	global_store_dwordx4 v10, v[20:23], s[26:27]
	s_add_i32 s23, s13, 8
	s_cmp_lt_u32 s23, 32
	s_cselect_b32 s23, s23, s13
	s_mul_i32 s0, s23, 0x40000
	s_add_u32 s26, s16, s0
	s_addc_u32 s27, s17, 0
	s_lshl_b32 s0, s23, 8
	s_add_u32 s28, s30, s0
	s_addc_u32 s29, s31, 0
	global_load_dwordx4 v[24:27], v5, s[26:27]
	global_load_dwordx4 v[28:31], v5, s[26:27] offset:16
	s_mov_b64 exec, s[24:25]
	global_load_dwordx4 v[32:35], v7, s[26:27]
	global_load_dwordx4 v[36:39], v7, s[26:27] offset:16
	global_load_dword v40, v11, s[28:29]
	s_mov_b64 exec, -1
	s_add_i32 s21, s13, 1
	s_waitcnt vmcnt(36)
	s_mov_b64 exec, s[24:25]
	v_pk_add_f32 v[42:43], v[42:43], v[50:51]
	v_pk_add_f32 v[44:45], v[44:45], v[52:53]
	v_pk_add_f32 v[46:47], v[46:47], v[54:55]
	v_pk_add_f32 v[48:49], v[48:49], v[56:57]
	v_pk_fma_f32 v[42:43], v[12:13], v[58:59], v[42:43] op_sel_hi:[1,0,1]
	v_pk_fma_f32 v[44:45], v[14:15], v[58:59], v[44:45] op_sel_hi:[1,0,1]
	v_pk_fma_f32 v[46:47], v[16:17], v[58:59], v[46:47] op_sel_hi:[1,0,1]
	v_pk_fma_f32 v[48:49], v[18:19], v[58:59], v[48:49] op_sel_hi:[1,0,1]
	s_mov_b64 exec, -1
	s_nop 0
	v_cvt_pk_bf16_f32 v20, v42, v43
	v_cvt_pk_bf16_f32 v21, v44, v45
	v_cvt_pk_bf16_f32 v22, v46, v47
	v_cvt_pk_bf16_f32 v23, v48, v49
	s_mul_i32 s0, s21, 0x300000
	s_add_u32 s26, s18, s0
	s_addc_u32 s27, s19, 0
	global_store_dwordx4 v10, v[20:23], s[26:27]
	s_add_i32 s23, s21, 8
	s_cmp_lt_u32 s23, 32
	s_cselect_b32 s23, s23, s21
	s_mul_i32 s0, s23, 0x40000
	s_add_u32 s26, s16, s0
	s_addc_u32 s27, s17, 0
	s_lshl_b32 s0, s23, 8
	s_add_u32 s28, s30, s0
	s_addc_u32 s29, s31, 0
	global_load_dwordx4 v[42:45], v5, s[26:27]
	global_load_dwordx4 v[46:49], v5, s[26:27] offset:16
	s_mov_b64 exec, s[24:25]
	global_load_dwordx4 v[50:53], v7, s[26:27]
	global_load_dwordx4 v[54:57], v7, s[26:27] offset:16
	global_load_dword v58, v11, s[28:29]
	s_mov_b64 exec, -1
	s_add_i32 s21, s13, 2
	s_waitcnt vmcnt(37)
	s_mov_b64 exec, s[24:25]
	v_pk_add_f32 v[60:61], v[60:61], v[68:69]
	v_pk_add_f32 v[62:63], v[62:63], v[70:71]
	v_pk_add_f32 v[64:65], v[64:65], v[72:73]
	v_pk_add_f32 v[66:67], v[66:67], v[74:75]
	v_pk_fma_f32 v[60:61], v[12:13], v[76:77], v[60:61] op_sel_hi:[1,0,1]
	v_pk_fma_f32 v[62:63], v[14:15], v[76:77], v[62:63] op_sel_hi:[1,0,1]
	v_pk_fma_f32 v[64:65], v[16:17], v[76:77], v[64:65] op_sel_hi:[1,0,1]
	v_pk_fma_f32 v[66:67], v[18:19], v[76:77], v[66:67] op_sel_hi:[1,0,1]
	s_mov_b64 exec, -1
	s_nop 0
	v_cvt_pk_bf16_f32 v20, v60, v61
	v_cvt_pk_bf16_f32 v21, v62, v63
	v_cvt_pk_bf16_f32 v22, v64, v65
	v_cvt_pk_bf16_f32 v23, v66, v67
	s_mul_i32 s0, s21, 0x300000
	s_add_u32 s26, s18, s0
	s_addc_u32 s27, s19, 0
	global_store_dwordx4 v10, v[20:23], s[26:27]
	s_add_i32 s23, s21, 8
	s_cmp_lt_u32 s23, 32
	s_cselect_b32 s23, s23, s21
	s_mul_i32 s0, s23, 0x40000
	s_add_u32 s26, s16, s0
	s_addc_u32 s27, s17, 0
	s_lshl_b32 s0, s23, 8
	s_add_u32 s28, s30, s0
	s_addc_u32 s29, s31, 0
	global_load_dwordx4 v[60:63], v5, s[26:27]
	global_load_dwordx4 v[64:67], v5, s[26:27] offset:16
	s_mov_b64 exec, s[24:25]
	global_load_dwordx4 v[68:71], v7, s[26:27]
	global_load_dwordx4 v[72:75], v7, s[26:27] offset:16
	global_load_dword v76, v11, s[28:29]
	s_mov_b64 exec, -1
	s_add_i32 s21, s13, 3
	s_waitcnt vmcnt(38)
	s_mov_b64 exec, s[24:25]
	v_pk_add_f32 v[78:79], v[78:79], v[86:87]
	v_pk_add_f32 v[80:81], v[80:81], v[88:89]
	v_pk_add_f32 v[82:83], v[82:83], v[90:91]
	v_pk_add_f32 v[84:85], v[84:85], v[92:93]
	v_pk_fma_f32 v[78:79], v[12:13], v[94:95], v[78:79] op_sel_hi:[1,0,1]
	v_pk_fma_f32 v[80:81], v[14:15], v[94:95], v[80:81] op_sel_hi:[1,0,1]
	v_pk_fma_f32 v[82:83], v[16:17], v[94:95], v[82:83] op_sel_hi:[1,0,1]
	v_pk_fma_f32 v[84:85], v[18:19], v[94:95], v[84:85] op_sel_hi:[1,0,1]
	s_mov_b64 exec, -1
	s_nop 0
	v_cvt_pk_bf16_f32 v20, v78, v79
	v_cvt_pk_bf16_f32 v21, v80, v81
	v_cvt_pk_bf16_f32 v22, v82, v83
	v_cvt_pk_bf16_f32 v23, v84, v85
	s_mul_i32 s0, s21, 0x300000
	s_add_u32 s26, s18, s0
	s_addc_u32 s27, s19, 0
	global_store_dwordx4 v10, v[20:23], s[26:27]
	s_add_i32 s23, s21, 8
	s_cmp_lt_u32 s23, 32
	s_cselect_b32 s23, s23, s21
	s_mul_i32 s0, s23, 0x40000
	s_add_u32 s26, s16, s0
	s_addc_u32 s27, s17, 0
	s_lshl_b32 s0, s23, 8
	s_add_u32 s28, s30, s0
	s_addc_u32 s29, s31, 0
	global_load_dwordx4 v[78:81], v5, s[26:27]
	global_load_dwordx4 v[82:85], v5, s[26:27] offset:16
	s_mov_b64 exec, s[24:25]
	global_load_dwordx4 v[86:89], v7, s[26:27]
	global_load_dwordx4 v[90:93], v7, s[26:27] offset:16
	global_load_dword v94, v11, s[28:29]
	s_mov_b64 exec, -1
	s_add_i32 s21, s13, 4
	s_waitcnt vmcnt(39)
; __device__ void phase_ymat_toeplitz(PP P, int wid) {
;     ...
;     for (size_t it = (size_t)blockIdx.x * NTHREADS + tidx; it < total; it += (size_t)gridDim.x * NTHREADS) {
;         const int k8 = (int)(it & 63) * 8, n = (int)(it >> 6) & 511, jg = (int)(it >> 15);
;         const int t = n >> 4, i = n & 15, s = k8 >> 4, j0 = k8 & 15;
;         const float* kf = ktab + ((size_t)jg * 2 + 0) * 32 * 256, *kb = ktab + ((size_t)jg * 2 + 1) * 32 * 256;
;         float f[8];
;         if (s < t) { load8f(kf + (t - s) * 256 + i * 16 + j0, f); }
;         else if (s > t) { load8f(kb + (s - t) * 256 + i * 16 + j0, f); }
;         else { float a[8], b[8]; load8f(kf + i * 16 + j0, a); load8f(kb + i * 16 + j0, b);
;             const int j = jg >> 6, g = jg & 63; const float dsk = P->in[21][j * D + g * 16 + i];
; #pragma unroll
;             for (int q = 0; q < 8; ++q) f[q] = a[q] + b[q] + ((j0 + q) == i ? dsk : 0.f); }
;         *(u32x4*)((bf16_t*)(P->ws + WS_YMAT) + ((size_t)jg * 512 + n) * XLD + k8) = pack8(f);
;     }
	s_mov_b64 exec, s[24:25]
	v_pk_add_f32 v[96:97], v[96:97], v[104:105]
	v_pk_add_f32 v[98:99], v[98:99], v[106:107]
	v_pk_add_f32 v[100:101], v[100:101], v[108:109]
	v_pk_add_f32 v[102:103], v[102:103], v[110:111]
	v_pk_fma_f32 v[96:97], v[12:13], v[112:113], v[96:97] op_sel_hi:[1,0,1]
	v_pk_fma_f32 v[98:99], v[14:15], v[112:113], v[98:99] op_sel_hi:[1,0,1]
	v_pk_fma_f32 v[100:101], v[16:17], v[112:113], v[100:101] op_sel_hi:[1,0,1]
	v_pk_fma_f32 v[102:103], v[18:19], v[112:113], v[102:103] op_sel_hi:[1,0,1]
	s_mov_b64 exec, -1
	s_nop 0
	v_cvt_pk_bf16_f32 v20, v96, v97
	v_cvt_pk_bf16_f32 v21, v98, v99
	v_cvt_pk_bf16_f32 v22, v100, v101
	v_cvt_pk_bf16_f32 v23, v102, v103
	s_mul_i32 s0, s21, 0x300000
	s_add_u32 s26, s18, s0
	s_addc_u32 s27, s19, 0
	global_store_dwordx4 v10, v[20:23], s[26:27]
	s_add_i32 s23, s21, 8
	s_cmp_lt_u32 s23, 32
	s_cselect_b32 s23, s23, s21
	s_mul_i32 s0, s23, 0x40000
	s_add_u32 s26, s16, s0
	s_addc_u32 s27, s17, 0
	s_lshl_b32 s0, s23, 8
	s_add_u32 s28, s30, s0
	s_addc_u32 s29, s31, 0
	global_load_dwordx4 v[96:99], v5, s[26:27]
	global_load_dwordx4 v[100:103], v5, s[26:27] offset:16
	s_mov_b64 exec, s[24:25]
	global_load_dwordx4 v[104:107], v7, s[26:27]
	global_load_dwordx4 v[108:111], v7, s[26:27] offset:16
	global_load_dword v112, v11, s[28:29]
	s_mov_b64 exec, -1
	s_add_i32 s21, s13, 5
	s_waitcnt vmcnt(40)
	s_mov_b64 exec, s[24:25]
	v_pk_add_f32 v[114:115], v[114:115], v[122:123]
	v_pk_add_f32 v[116:117], v[116:117], v[124:125]
	v_pk_add_f32 v[118:119], v[118:119], v[126:127]
	v_pk_add_f32 v[120:121], v[120:121], v[128:129]
	v_pk_fma_f32 v[114:115], v[12:13], v[130:131], v[114:115] op_sel_hi:[1,0,1]
	v_pk_fma_f32 v[116:117], v[14:15], v[130:131], v[116:117] op_sel_hi:[1,0,1]
	v_pk_fma_f32 v[118:119], v[16:17], v[130:131], v[118:119] op_sel_hi:[1,0,1]
	v_pk_fma_f32 v[120:121], v[18:19], v[130:131], v[120:121] op_sel_hi:[1,0,1]
	s_mov_b64 exec, -1
	s_nop 0
	v_cvt_pk_bf16_f32 v20, v114, v115
	v_cvt_pk_bf16_f32 v21, v116, v117
	v_cvt_pk_bf16_f32 v22, v118, v119
	v_cvt_pk_bf16_f32 v23, v120, v121
	s_mul_i32 s0, s21, 0x300000
	s_add_u32 s26, s18, s0
	s_addc_u32 s27, s19, 0
	global_store_dwordx4 v10, v[20:23], s[26:27]
	s_add_i32 s23, s21, 8
	s_cmp_lt_u32 s23, 32
	s_cselect_b32 s23, s23, s21
	s_mul_i32 s0, s23, 0x40000
	s_add_u32 s26, s16, s0
	s_addc_u32 s27, s17, 0
	s_lshl_b32 s0, s23, 8
	s_add_u32 s28, s30, s0
	s_addc_u32 s29, s31, 0
	global_load_dwordx4 v[114:117], v5, s[26:27]
	global_load_dwordx4 v[118:121], v5, s[26:27] offset:16
	s_mov_b64 exec, s[24:25]
	global_load_dwordx4 v[122:125], v7, s[26:27]
	global_load_dwordx4 v[126:129], v7, s[26:27] offset:16
	global_load_dword v130, v11, s[28:29]
	s_mov_b64 exec, -1
	s_add_i32 s21, s13, 6
	s_waitcnt vmcnt(41)
	s_mov_b64 exec, s[24:25]
	v_pk_add_f32 v[132:133], v[132:133], v[140:141]
	v_pk_add_f32 v[134:135], v[134:135], v[142:143]
	v_pk_add_f32 v[136:137], v[136:137], v[144:145]
	v_pk_add_f32 v[138:139], v[138:139], v[146:147]
	v_pk_fma_f32 v[132:133], v[12:13], v[148:149], v[132:133] op_sel_hi:[1,0,1]
	v_pk_fma_f32 v[134:135], v[14:15], v[148:149], v[134:135] op_sel_hi:[1,0,1]
	v_pk_fma_f32 v[136:137], v[16:17], v[148:149], v[136:137] op_sel_hi:[1,0,1]
	v_pk_fma_f32 v[138:139], v[18:19], v[148:149], v[138:139] op_sel_hi:[1,0,1]
	s_mov_b64 exec, -1
	s_nop 0
	v_cvt_pk_bf16_f32 v20, v132, v133
	v_cvt_pk_bf16_f32 v21, v134, v135
	v_cvt_pk_bf16_f32 v22, v136, v137
	v_cvt_pk_bf16_f32 v23, v138, v139
	s_mul_i32 s0, s21, 0x300000
	s_add_u32 s26, s18, s0
	s_addc_u32 s27, s19, 0
	global_store_dwordx4 v10, v[20:23], s[26:27]
	s_add_i32 s23, s21, 8
	s_cmp_lt_u32 s23, 32
	s_cselect_b32 s23, s23, s21
	s_mul_i32 s0, s23, 0x40000
	s_add_u32 s26, s16, s0
	s_addc_u32 s27, s17, 0
	s_lshl_b32 s0, s23, 8
	s_add_u32 s28, s30, s0
	s_addc_u32 s29, s31, 0
	global_load_dwordx4 v[132:135], v5, s[26:27]
	global_load_dwordx4 v[136:139], v5, s[26:27] offset:16
	s_mov_b64 exec, s[24:25]
	global_load_dwordx4 v[140:143], v7, s[26:27]
	global_load_dwordx4 v[144:147], v7, s[26:27] offset:16
	global_load_dword v148, v11, s[28:29]
	s_mov_b64 exec, -1
	s_add_i32 s21, s13, 7
	s_waitcnt vmcnt(42)
	s_mov_b64 exec, s[24:25]
	v_pk_add_f32 v[150:151], v[150:151], v[158:159]
	v_pk_add_f32 v[152:153], v[152:153], v[160:161]
	v_pk_add_f32 v[154:155], v[154:155], v[162:163]
	v_pk_add_f32 v[156:157], v[156:157], v[164:165]
	v_pk_fma_f32 v[150:151], v[12:13], v[166:167], v[150:151] op_sel_hi:[1,0,1]
	v_pk_fma_f32 v[152:153], v[14:15], v[166:167], v[152:153] op_sel_hi:[1,0,1]
	v_pk_fma_f32 v[154:155], v[16:17], v[166:167], v[154:155] op_sel_hi:[1,0,1]
	v_pk_fma_f32 v[156:157], v[18:19], v[166:167], v[156:157] op_sel_hi:[1,0,1]
	s_mov_b64 exec, -1
	s_nop 0
	v_cvt_pk_bf16_f32 v20, v150, v151
	v_cvt_pk_bf16_f32 v21, v152, v153
	v_cvt_pk_bf16_f32 v22, v154, v155
	v_cvt_pk_bf16_f32 v23, v156, v157
	s_mul_i32 s0, s21, 0x300000
	s_add_u32 s26, s18, s0
	s_addc_u32 s27, s19, 0
	global_store_dwordx4 v10, v[20:23], s[26:27]
	s_add_i32 s23, s21, 8
	s_cmp_lt_u32 s23, 32
	s_cselect_b32 s23, s23, s21
	s_mul_i32 s0, s23, 0x40000
	s_add_u32 s26, s16, s0
	s_addc_u32 s27, s17, 0
	s_lshl_b32 s0, s23, 8
	s_add_u32 s28, s30, s0
	s_addc_u32 s29, s31, 0
	global_load_dwordx4 v[150:153], v5, s[26:27]
	global_load_dwordx4 v[154:157], v5, s[26:27] offset:16
	s_mov_b64 exec, s[24:25]
	global_load_dwordx4 v[158:161], v7, s[26:27]
	global_load_dwordx4 v[162:165], v7, s[26:27] offset:16
	global_load_dword v166, v11, s[28:29]
	s_mov_b64 exec, -1
	s_mov_b32 s13, 8
; __device__ void phase_ymat_toeplitz(PP P, int wid) {
;     ...
;     for (size_t it = (size_t)blockIdx.x * NTHREADS + tidx; it < total; it += (size_t)gridDim.x * NTHREADS) {
;         const int k8 = (int)(it & 63) * 8, n = (int)(it >> 6) & 511, jg = (int)(it >> 15);
;         const int t = n >> 4, i = n & 15, s = k8 >> 4, j0 = k8 & 15;
;         const float* kf = ktab + ((size_t)jg * 2 + 0) * 32 * 256, *kb = ktab + ((size_t)jg * 2 + 1) * 32 * 256;
;         float f[8];
;         if (s < t) { load8f(kf + (t - s) * 256 + i * 16 + j0, f); }
;         else if (s > t) { load8f(kb + (s - t) * 256 + i * 16 + j0, f); }
;         else { float a[8], b[8]; load8f(kf + i * 16 + j0, a); load8f(kb + i * 16 + j0, b);
;             const int j = jg >> 6, g = jg & 63; const float dsk = P->in[21][j * D + g * 16 + i];
; #pragma unroll
;             for (int q = 0; q < 8; ++q) f[q] = a[q] + b[q] + ((j0 + q) == i ? dsk : 0.f); }
;         *(u32x4*)((bf16_t*)(P->ws + WS_YMAT) + ((size_t)jg * 512 + n) * XLD + k8) = pack8(f);
;     }
.Ltp_loop:
	s_waitcnt vmcnt(42)
	s_mov_b64 exec, s[24:25]
	v_pk_add_f32 v[24:25], v[24:25], v[32:33]
	v_pk_add_f32 v[26:27], v[26:27], v[34:35]
	v_pk_add_f32 v[28:29], v[28:29], v[36:37]
	v_pk_add_f32 v[30:31], v[30:31], v[38:39]
	v_pk_fma_f32 v[24:25], v[12:13], v[40:41], v[24:25] op_sel_hi:[1,0,1]
	v_pk_fma_f32 v[26:27], v[14:15], v[40:41], v[26:27] op_sel_hi:[1,0,1]
	v_pk_fma_f32 v[28:29], v[16:17], v[40:41], v[28:29] op_sel_hi:[1,0,1]
	v_pk_fma_f32 v[30:31], v[18:19], v[40:41], v[30:31] op_sel_hi:[1,0,1]
	s_mov_b64 exec, -1
	s_nop 0
	v_cvt_pk_bf16_f32 v20, v24, v25
	v_cvt_pk_bf16_f32 v21, v26, v27
	v_cvt_pk_bf16_f32 v22, v28, v29
	v_cvt_pk_bf16_f32 v23, v30, v31
	s_mul_i32 s0, s13, 0x300000
	s_add_u32 s26, s18, s0
	s_addc_u32 s27, s19, 0
	global_store_dwordx4 v10, v[20:23], s[26:27]
	s_add_i32 s23, s13, 8
	s_cmp_lt_u32 s23, 32
	s_cselect_b32 s23, s23, s13
	s_mul_i32 s0, s23, 0x40000
	s_add_u32 s26, s16, s0
	s_addc_u32 s27, s17, 0
	s_lshl_b32 s0, s23, 8
	s_add_u32 s28, s30, s0
	s_addc_u32 s29, s31, 0
	global_load_dwordx4 v[24:27], v5, s[26:27]
	global_load_dwordx4 v[28:31], v5, s[26:27] offset:16
	s_mov_b64 exec, s[24:25]
	global_load_dwordx4 v[32:35], v7, s[26:27]
	global_load_dwordx4 v[36:39], v7, s[26:27] offset:16
	global_load_dword v40, v11, s[28:29]
	s_mov_b64 exec, -1
	s_add_i32 s21, s13, 1
	s_waitcnt vmcnt(42)
	s_mov_b64 exec, s[24:25]
	v_pk_add_f32 v[42:43], v[42:43], v[50:51]
	v_pk_add_f32 v[44:45], v[44:45], v[52:53]
	v_pk_add_f32 v[46:47], v[46:47], v[54:55]
	v_pk_add_f32 v[48:49], v[48:49], v[56:57]
	v_pk_fma_f32 v[42:43], v[12:13], v[58:59], v[42:43] op_sel_hi:[1,0,1]
	v_pk_fma_f32 v[44:45], v[14:15], v[58:59], v[44:45] op_sel_hi:[1,0,1]
	v_pk_fma_f32 v[46:47], v[16:17], v[58:59], v[46:47] op_sel_hi:[1,0,1]
	v_pk_fma_f32 v[48:49], v[18:19], v[58:59], v[48:49] op_sel_hi:[1,0,1]
	s_mov_b64 exec, -1
	s_nop 0
	v_cvt_pk_bf16_f32 v20, v42, v43
	v_cvt_pk_bf16_f32 v21, v44, v45
	v_cvt_pk_bf16_f32 v22, v46, v47
	v_cvt_pk_bf16_f32 v23, v48, v49
	s_mul_i32 s0, s21, 0x300000
	s_add_u32 s26, s18, s0
	s_addc_u32 s27, s19, 0
	global_store_dwordx4 v10, v[20:23], s[26:27]
	s_add_i32 s23, s21, 8
	s_cmp_lt_u32 s23, 32
	s_cselect_b32 s23, s23, s21
	s_mul_i32 s0, s23, 0x40000
	s_add_u32 s26, s16, s0
	s_addc_u32 s27, s17, 0
	s_lshl_b32 s0, s23, 8
	s_add_u32 s28, s30, s0
	s_addc_u32 s29, s31, 0
	global_load_dwordx4 v[42:45], v5, s[26:27]
	global_load_dwordx4 v[46:49], v5, s[26:27] offset:16
	s_mov_b64 exec, s[24:25]
	global_load_dwordx4 v[50:53], v7, s[26:27]
	global_load_dwordx4 v[54:57], v7, s[26:27] offset:16
	global_load_dword v58, v11, s[28:29]
	s_mov_b64 exec, -1
	s_add_i32 s21, s13, 2
	s_waitcnt vmcnt(42)
	s_mov_b64 exec, s[24:25]
	v_pk_add_f32 v[60:61], v[60:61], v[68:69]
	v_pk_add_f32 v[62:63], v[62:63], v[70:71]
	v_pk_add_f32 v[64:65], v[64:65], v[72:73]
	v_pk_add_f32 v[66:67], v[66:67], v[74:75]
	v_pk_fma_f32 v[60:61], v[12:13], v[76:77], v[60:61] op_sel_hi:[1,0,1]
	v_pk_fma_f32 v[62:63], v[14:15], v[76:77], v[62:63] op_sel_hi:[1,0,1]
	v_pk_fma_f32 v[64:65], v[16:17], v[76:77], v[64:65] op_sel_hi:[1,0,1]
	v_pk_fma_f32 v[66:67], v[18:19], v[76:77], v[66:67] op_sel_hi:[1,0,1]
	s_mov_b64 exec, -1
	s_nop 0
	v_cvt_pk_bf16_f32 v20, v60, v61
	v_cvt_pk_bf16_f32 v21, v62, v63
	v_cvt_pk_bf16_f32 v22, v64, v65
	v_cvt_pk_bf16_f32 v23, v66, v67
	s_mul_i32 s0, s21, 0x300000
	s_add_u32 s26, s18, s0
	s_addc_u32 s27, s19, 0
	global_store_dwordx4 v10, v[20:23], s[26:27]
	s_add_i32 s23, s21, 8
	s_cmp_lt_u32 s23, 32
	s_cselect_b32 s23, s23, s21
	s_mul_i32 s0, s23, 0x40000
	s_add_u32 s26, s16, s0
	s_addc_u32 s27, s17, 0
	s_lshl_b32 s0, s23, 8
	s_add_u32 s28, s30, s0
	s_addc_u32 s29, s31, 0
	global_load_dwordx4 v[60:63], v5, s[26:27]
	global_load_dwordx4 v[64:67], v5, s[26:27] offset:16
	s_mov_b64 exec, s[24:25]
	global_load_dwordx4 v[68:71], v7, s[26:27]
	global_load_dwordx4 v[72:75], v7, s[26:27] offset:16
	global_load_dword v76, v11, s[28:29]
	s_mov_b64 exec, -1
	s_add_i32 s21, s13, 3
	s_waitcnt vmcnt(42)
	s_mov_b64 exec, s[24:25]
	v_pk_add_f32 v[78:79], v[78:79], v[86:87]
	v_pk_add_f32 v[80:81], v[80:81], v[88:89]
	v_pk_add_f32 v[82:83], v[82:83], v[90:91]
	v_pk_add_f32 v[84:85], v[84:85], v[92:93]
	v_pk_fma_f32 v[78:79], v[12:13], v[94:95], v[78:79] op_sel_hi:[1,0,1]
	v_pk_fma_f32 v[80:81], v[14:15], v[94:95], v[80:81] op_sel_hi:[1,0,1]
	v_pk_fma_f32 v[82:83], v[16:17], v[94:95], v[82:83] op_sel_hi:[1,0,1]
	v_pk_fma_f32 v[84:85], v[18:19], v[94:95], v[84:85] op_sel_hi:[1,0,1]
	s_mov_b64 exec, -1
	s_nop 0
	v_cvt_pk_bf16_f32 v20, v78, v79
	v_cvt_pk_bf16_f32 v21, v80, v81
	v_cvt_pk_bf16_f32 v22, v82, v83
	v_cvt_pk_bf16_f32 v23, v84, v85
	s_mul_i32 s0, s21, 0x300000
	s_add_u32 s26, s18, s0
	s_addc_u32 s27, s19, 0
	global_store_dwordx4 v10, v[20:23], s[26:27]
	s_add_i32 s23, s21, 8
	s_cmp_lt_u32 s23, 32
	s_cselect_b32 s23, s23, s21
	s_mul_i32 s0, s23, 0x40000
	s_add_u32 s26, s16, s0
	s_addc_u32 s27, s17, 0
	s_lshl_b32 s0, s23, 8
	s_add_u32 s28, s30, s0
	s_addc_u32 s29, s31, 0
	global_load_dwordx4 v[78:81], v5, s[26:27]
	global_load_dwordx4 v[82:85], v5, s[26:27] offset:16
	s_mov_b64 exec, s[24:25]
	global_load_dwordx4 v[86:89], v7, s[26:27]
	global_load_dwordx4 v[90:93], v7, s[26:27] offset:16
	global_load_dword v94, v11, s[28:29]
	s_mov_b64 exec, -1
	s_add_i32 s21, s13, 4
	s_waitcnt vmcnt(42)
; __device__ void phase_ymat_toeplitz(PP P, int wid) {
;     ...
;     for (size_t it = (size_t)blockIdx.x * NTHREADS + tidx; it < total; it += (size_t)gridDim.x * NTHREADS) {
;         const int k8 = (int)(it & 63) * 8, n = (int)(it >> 6) & 511, jg = (int)(it >> 15);
;         const int t = n >> 4, i = n & 15, s = k8 >> 4, j0 = k8 & 15;
;         const float* kf = ktab + ((size_t)jg * 2 + 0) * 32 * 256, *kb = ktab + ((size_t)jg * 2 + 1) * 32 * 256;
;         float f[8];
;         if (s < t) { load8f(kf + (t - s) * 256 + i * 16 + j0, f); }
;         else if (s > t) { load8f(kb + (s - t) * 256 + i * 16 + j0, f); }
;         else { float a[8], b[8]; load8f(kf + i * 16 + j0, a); load8f(kb + i * 16 + j0, b);
;             const int j = jg >> 6, g = jg & 63; const float dsk = P->in[21][j * D + g * 16 + i];
; #pragma unroll
;             for (int q = 0; q < 8; ++q) f[q] = a[q] + b[q] + ((j0 + q) == i ? dsk : 0.f); }
;         *(u32x4*)((bf16_t*)(P->ws + WS_YMAT) + ((size_t)jg * 512 + n) * XLD + k8) = pack8(f);
	s_mov_b64 exec, s[24:25]
	v_pk_add_f32 v[96:97], v[96:97], v[104:105]
	v_pk_add_f32 v[98:99], v[98:99], v[106:107]
	v_pk_add_f32 v[100:101], v[100:101], v[108:109]
	v_pk_add_f32 v[102:103], v[102:103], v[110:111]
	v_pk_fma_f32 v[96:97], v[12:13], v[112:113], v[96:97] op_sel_hi:[1,0,1]
	v_pk_fma_f32 v[98:99], v[14:15], v[112:113], v[98:99] op_sel_hi:[1,0,1]
	v_pk_fma_f32 v[100:101], v[16:17], v[112:113], v[100:101] op_sel_hi:[1,0,1]
	v_pk_fma_f32 v[102:103], v[18:19], v[112:113], v[102:103] op_sel_hi:[1,0,1]
	s_mov_b64 exec, -1
	s_nop 0
	v_cvt_pk_bf16_f32 v20, v96, v97
	v_cvt_pk_bf16_f32 v21, v98, v99
	v_cvt_pk_bf16_f32 v22, v100, v101
	v_cvt_pk_bf16_f32 v23, v102, v103
	s_mul_i32 s0, s21, 0x300000
	s_add_u32 s26, s18, s0
	s_addc_u32 s27, s19, 0
	global_store_dwordx4 v10, v[20:23], s[26:27]
	s_add_i32 s23, s21, 8
	s_cmp_lt_u32 s23, 32
	s_cselect_b32 s23, s23, s21
	s_mul_i32 s0, s23, 0x40000
	s_add_u32 s26, s16, s0
	s_addc_u32 s27, s17, 0
	s_lshl_b32 s0, s23, 8
	s_add_u32 s28, s30, s0
	s_addc_u32 s29, s31, 0
	global_load_dwordx4 v[96:99], v5, s[26:27]
	global_load_dwordx4 v[100:103], v5, s[26:27] offset:16
	s_mov_b64 exec, s[24:25]
	global_load_dwordx4 v[104:107], v7, s[26:27]
	global_load_dwordx4 v[108:111], v7, s[26:27] offset:16
	global_load_dword v112, v11, s[28:29]
	s_mov_b64 exec, -1
	s_add_i32 s21, s13, 5
	s_waitcnt vmcnt(42)
	s_mov_b64 exec, s[24:25]
	v_pk_add_f32 v[114:115], v[114:115], v[122:123]
	v_pk_add_f32 v[116:117], v[116:117], v[124:125]
	v_pk_add_f32 v[118:119], v[118:119], v[126:127]
	v_pk_add_f32 v[120:121], v[120:121], v[128:129]
	v_pk_fma_f32 v[114:115], v[12:13], v[130:131], v[114:115] op_sel_hi:[1,0,1]
	v_pk_fma_f32 v[116:117], v[14:15], v[130:131], v[116:117] op_sel_hi:[1,0,1]
	v_pk_fma_f32 v[118:119], v[16:17], v[130:131], v[118:119] op_sel_hi:[1,0,1]
	v_pk_fma_f32 v[120:121], v[18:19], v[130:131], v[120:121] op_sel_hi:[1,0,1]
	s_mov_b64 exec, -1
	s_nop 0
	v_cvt_pk_bf16_f32 v20, v114, v115
	v_cvt_pk_bf16_f32 v21, v116, v117
	v_cvt_pk_bf16_f32 v22, v118, v119
	v_cvt_pk_bf16_f32 v23, v120, v121
	s_mul_i32 s0, s21, 0x300000
	s_add_u32 s26, s18, s0
	s_addc_u32 s27, s19, 0
	global_store_dwordx4 v10, v[20:23], s[26:27]
	s_add_i32 s23, s21, 8
	s_cmp_lt_u32 s23, 32
	s_cselect_b32 s23, s23, s21
	s_mul_i32 s0, s23, 0x40000
	s_add_u32 s26, s16, s0
	s_addc_u32 s27, s17, 0
	s_lshl_b32 s0, s23, 8
	s_add_u32 s28, s30, s0
	s_addc_u32 s29, s31, 0
	global_load_dwordx4 v[114:117], v5, s[26:27]
	global_load_dwordx4 v[118:121], v5, s[26:27] offset:16
	s_mov_b64 exec, s[24:25]
	global_load_dwordx4 v[122:125], v7, s[26:27]
	global_load_dwordx4 v[126:129], v7, s[26:27] offset:16
	global_load_dword v130, v11, s[28:29]
	s_mov_b64 exec, -1
	s_add_i32 s21, s13, 6
	s_waitcnt vmcnt(42)
	s_mov_b64 exec, s[24:25]
	v_pk_add_f32 v[132:133], v[132:133], v[140:141]
	v_pk_add_f32 v[134:135], v[134:135], v[142:143]
	v_pk_add_f32 v[136:137], v[136:137], v[144:145]
	v_pk_add_f32 v[138:139], v[138:139], v[146:147]
	v_pk_fma_f32 v[132:133], v[12:13], v[148:149], v[132:133] op_sel_hi:[1,0,1]
	v_pk_fma_f32 v[134:135], v[14:15], v[148:149], v[134:135] op_sel_hi:[1,0,1]
	v_pk_fma_f32 v[136:137], v[16:17], v[148:149], v[136:137] op_sel_hi:[1,0,1]
	v_pk_fma_f32 v[138:139], v[18:19], v[148:149], v[138:139] op_sel_hi:[1,0,1]
	s_mov_b64 exec, -1
	s_nop 0
	v_cvt_pk_bf16_f32 v20, v132, v133
	v_cvt_pk_bf16_f32 v21, v134, v135
	v_cvt_pk_bf16_f32 v22, v136, v137
	v_cvt_pk_bf16_f32 v23, v138, v139
	s_mul_i32 s0, s21, 0x300000
	s_add_u32 s26, s18, s0
	s_addc_u32 s27, s19, 0
	global_store_dwordx4 v10, v[20:23], s[26:27]
	s_add_i32 s23, s21, 8
	s_cmp_lt_u32 s23, 32
	s_cselect_b32 s23, s23, s21
	s_mul_i32 s0, s23, 0x40000
	s_add_u32 s26, s16, s0
	s_addc_u32 s27, s17, 0
	s_lshl_b32 s0, s23, 8
	s_add_u32 s28, s30, s0
	s_addc_u32 s29, s31, 0
	global_load_dwordx4 v[132:135], v5, s[26:27]
	global_load_dwordx4 v[136:139], v5, s[26:27] offset:16
	s_mov_b64 exec, s[24:25]
	global_load_dwordx4 v[140:143], v7, s[26:27]
	global_load_dwordx4 v[144:147], v7, s[26:27] offset:16
	global_load_dword v148, v11, s[28:29]
	s_mov_b64 exec, -1
	s_add_i32 s21, s13, 7
	s_waitcnt vmcnt(42)
	s_mov_b64 exec, s[24:25]
	v_pk_add_f32 v[150:151], v[150:151], v[158:159]
	v_pk_add_f32 v[152:153], v[152:153], v[160:161]
	v_pk_add_f32 v[154:155], v[154:155], v[162:163]
	v_pk_add_f32 v[156:157], v[156:157], v[164:165]
	v_pk_fma_f32 v[150:151], v[12:13], v[166:167], v[150:151] op_sel_hi:[1,0,1]
	v_pk_fma_f32 v[152:153], v[14:15], v[166:167], v[152:153] op_sel_hi:[1,0,1]
	v_pk_fma_f32 v[154:155], v[16:17], v[166:167], v[154:155] op_sel_hi:[1,0,1]
	v_pk_fma_f32 v[156:157], v[18:19], v[166:167], v[156:157] op_sel_hi:[1,0,1]
	s_mov_b64 exec, -1
	s_nop 0
	v_cvt_pk_bf16_f32 v20, v150, v151
	v_cvt_pk_bf16_f32 v21, v152, v153
	v_cvt_pk_bf16_f32 v22, v154, v155
	v_cvt_pk_bf16_f32 v23, v156, v157
	s_mul_i32 s0, s21, 0x300000
	s_add_u32 s26, s18, s0
	s_addc_u32 s27, s19, 0
	global_store_dwordx4 v10, v[20:23], s[26:27]
	s_add_i32 s23, s21, 8
	s_cmp_lt_u32 s23, 32
	s_cselect_b32 s23, s23, s21
	s_mul_i32 s0, s23, 0x40000
	s_add_u32 s26, s16, s0
	s_addc_u32 s27, s17, 0
	s_lshl_b32 s0, s23, 8
	s_add_u32 s28, s30, s0
	s_addc_u32 s29, s31, 0
	global_load_dwordx4 v[150:153], v5, s[26:27]
	global_load_dwordx4 v[154:157], v5, s[26:27] offset:16
	s_mov_b64 exec, s[24:25]
	global_load_dwordx4 v[158:161], v7, s[26:27]
	global_load_dwordx4 v[162:165], v7, s[26:27] offset:16
	global_load_dword v166, v11, s[28:29]
	s_mov_b64 exec, -1
	s_add_i32 s13, s13, 8
	s_cmp_lt_u32 s13, 32
	s_cbranch_scc1 .Ltp_loop
	s_waitcnt vmcnt(0)
	s_branch .LBB0_107
